# main G1 K loop: LDS-DMA loads use the SADDR form (SGPR base pair + 32-bit lane offset) instead of a VALU 64-bit address add per load; 16 VALU ops per iteration removed from the load segments
# speedup vs baseline: 1.0028x; 1.0028x over previous
.LBB0_57:
	s_add_u32 s4, s0, 0xfffc0080
	s_addc_u32 s5, s1, -1
	s_add_i32 s17, 0, 0x10000
	s_cmp_eq_u32 s16, 12
	s_cselect_b32 s7, s9, s5
	s_cselect_b32 s6, s11, s4
	v_add_u32_e32 v0, s17, v198
	s_cselect_b32 s5, s12, s15
	s_cselect_b32 s4, s13, s14
	s_add_i32 s20, 0, 0x14000
	ds_read_b128 v[18:21], v0
	ds_read_b128 v[22:25], v0 offset:1024
	ds_read_b128 v[34:37], v0 offset:2048
	ds_read_b128 v[38:41], v0 offset:3072
	v_add_u32_e32 v0, s20, v198
	ds_read_b128 v[146:149], v0
	ds_read_b128 v[150:153], v0 offset:1024
	ds_read_b128 v[172:175], v0 offset:2048
	ds_read_b128 v[176:179], v0 offset:3072
	s_add_i32 m0, s69, 0xc000
	ds_read_b128 v[180:183], v200
	ds_read_b128 v[184:187], v200 offset:1024
	ds_read_b128 v[202:205], v200 offset:2048
	ds_read_b128 v[206:209], v200 offset:3072
	ds_read_b128 v[210:213], v200 offset:4096
	ds_read_b128 v[214:217], v200 offset:5120
	ds_read_b128 v[218:221], v200 offset:6144
	ds_read_b128 v[234:237], v200 offset:7168
	global_load_lds_dwordx4 v168, s[0:1]
	s_add_i32 m0, s69, 0xe000
	s_nop 0
	global_load_lds_dwordx4 v170, s[0:1]
	s_waitcnt vmcnt(8)
	s_waitcnt lgkmcnt(0)
	s_barrier
	s_setprio 1
	s_waitcnt lgkmcnt(0)
	v_mfma_f32_16x16x32_bf16 v[142:145], v[18:21], v[180:183], v[142:145]
	v_mfma_f32_16x16x32_bf16 v[138:141], v[34:37], v[180:183], v[138:141]
	v_mfma_f32_16x16x32_bf16 v[126:129], v[18:21], v[202:205], v[126:129]
	v_mfma_f32_16x16x32_bf16 v[122:125], v[34:37], v[202:205], v[122:125]
	v_mfma_f32_16x16x32_bf16 v[110:113], v[18:21], v[210:213], v[110:113]
	v_mfma_f32_16x16x32_bf16 v[106:109], v[34:37], v[210:213], v[106:109]
	v_mfma_f32_16x16x32_bf16 v[94:97], v[18:21], v[218:221], v[94:97]
	v_mfma_f32_16x16x32_bf16 v[90:93], v[34:37], v[218:221], v[90:93]
	v_mfma_f32_16x16x32_bf16 v[142:145], v[22:25], v[184:187], v[142:145]
	v_mfma_f32_16x16x32_bf16 v[138:141], v[38:41], v[184:187], v[138:141]
	v_mfma_f32_16x16x32_bf16 v[126:129], v[22:25], v[206:209], v[126:129]
	v_mfma_f32_16x16x32_bf16 v[122:125], v[38:41], v[206:209], v[122:125]
	v_mfma_f32_16x16x32_bf16 v[110:113], v[22:25], v[214:217], v[110:113]
	v_mfma_f32_16x16x32_bf16 v[106:109], v[38:41], v[214:217], v[106:109]
	v_mfma_f32_16x16x32_bf16 v[94:97], v[22:25], v[234:237], v[94:97]
	v_mfma_f32_16x16x32_bf16 v[90:93], v[38:41], v[234:237], v[90:93]
	s_setprio 0
	s_setprio 1
	v_mfma_f32_16x16x32_bf16 v[134:137], v[146:149], v[180:183], v[134:137]
	v_mfma_f32_16x16x32_bf16 v[130:133], v[172:175], v[180:183], v[130:133]
	v_mfma_f32_16x16x32_bf16 v[118:121], v[146:149], v[202:205], v[118:121]
	v_mfma_f32_16x16x32_bf16 v[114:117], v[172:175], v[202:205], v[114:117]
	v_mfma_f32_16x16x32_bf16 v[102:105], v[146:149], v[210:213], v[102:105]
	v_mfma_f32_16x16x32_bf16 v[98:101], v[172:175], v[210:213], v[98:101]
	v_mfma_f32_16x16x32_bf16 v[86:89], v[146:149], v[218:221], v[86:89]
	v_mfma_f32_16x16x32_bf16 v[82:85], v[172:175], v[218:221], v[82:85]
	v_mfma_f32_16x16x32_bf16 v[134:137], v[150:153], v[184:187], v[134:137]
	v_mfma_f32_16x16x32_bf16 v[130:133], v[176:179], v[184:187], v[130:133]
	v_mfma_f32_16x16x32_bf16 v[118:121], v[150:153], v[206:209], v[118:121]
	v_mfma_f32_16x16x32_bf16 v[114:117], v[176:179], v[206:209], v[114:117]
	v_mfma_f32_16x16x32_bf16 v[102:105], v[150:153], v[214:217], v[102:105]
	v_mfma_f32_16x16x32_bf16 v[98:101], v[176:179], v[214:217], v[98:101]
	v_mfma_f32_16x16x32_bf16 v[86:89], v[150:153], v[234:237], v[86:89]
	v_mfma_f32_16x16x32_bf16 v[82:85], v[176:179], v[234:237], v[82:85]
	s_setprio 0
	s_barrier
	s_add_i32 s17, s17, s87
	s_mov_b32 m0, s17
	ds_read_b128 v[180:183], v200 offset:16384
	ds_read_b128 v[184:187], v200 offset:17408
	ds_read_b128 v[202:205], v200 offset:18432
	ds_read_b128 v[206:209], v200 offset:19456
	ds_read_b128 v[210:213], v200 offset:20480
	ds_read_b128 v[214:217], v200 offset:21504
	ds_read_b128 v[218:221], v200 offset:22528
	ds_read_b128 v[234:237], v200 offset:23552
	global_load_lds_dwordx4 v158, s[4:5]
	s_add_i32 m0, s17, 0x2000
	s_add_u32 s98, s6, s48
	s_addc_u32 s99, s7, s49
	s_add_u32 s18, s4, 0x40000
	s_addc_u32 s19, s5, 0
	s_add_i32 s17, s20, s87
	global_load_lds_dwordx4 v154, s[4:5]
	s_mov_b32 m0, s17
	s_nop 0
	global_load_lds_dwordx4 v158, s[18:19]
	s_add_i32 m0, s17, 0x2000
	s_nop 0
	global_load_lds_dwordx4 v154, s[18:19]
	s_mov_b32 m0, s69
	s_nop 0
	global_load_lds_dwordx4 v160, s[6:7]
	s_mov_b32 m0, s76
	s_nop 0
	global_load_lds_dwordx4 v156, s[6:7]
	s_waitcnt vmcnt(8)
	s_waitcnt lgkmcnt(0)
	s_barrier
	s_setprio 1
	s_waitcnt lgkmcnt(0)
	v_mfma_f32_16x16x32_bf16 v[78:81], v[18:21], v[180:183], v[78:81]
	v_mfma_f32_16x16x32_bf16 v[74:77], v[34:37], v[180:183], v[74:77]
	v_mfma_f32_16x16x32_bf16 v[62:65], v[18:21], v[202:205], v[62:65]
	v_mfma_f32_16x16x32_bf16 v[58:61], v[34:37], v[202:205], v[58:61]
	v_mfma_f32_16x16x32_bf16 v[46:49], v[18:21], v[210:213], v[46:49]
	v_mfma_f32_16x16x32_bf16 v[42:45], v[34:37], v[210:213], v[42:45]
	v_mfma_f32_16x16x32_bf16 v[14:17], v[18:21], v[218:221], v[14:17]
	v_mfma_f32_16x16x32_bf16 v[10:13], v[34:37], v[218:221], v[10:13]
	v_mfma_f32_16x16x32_bf16 v[78:81], v[22:25], v[184:187], v[78:81]
	v_mfma_f32_16x16x32_bf16 v[74:77], v[38:41], v[184:187], v[74:77]
	v_mfma_f32_16x16x32_bf16 v[62:65], v[22:25], v[206:209], v[62:65]
	v_mfma_f32_16x16x32_bf16 v[58:61], v[38:41], v[206:209], v[58:61]
	v_mfma_f32_16x16x32_bf16 v[46:49], v[22:25], v[214:217], v[46:49]
	v_mfma_f32_16x16x32_bf16 v[42:45], v[38:41], v[214:217], v[42:45]
	v_mfma_f32_16x16x32_bf16 v[14:17], v[22:25], v[234:237], v[14:17]
	v_mfma_f32_16x16x32_bf16 v[10:13], v[38:41], v[234:237], v[10:13]
	s_setprio 0
	s_setprio 1
	v_mfma_f32_16x16x32_bf16 v[30:33], v[146:149], v[210:213], v[30:33]
	v_mfma_f32_16x16x32_bf16 v[26:29], v[172:175], v[210:213], v[26:29]
	v_mfma_f32_16x16x32_bf16 v[6:9], v[146:149], v[218:221], v[6:9]
	v_mfma_f32_16x16x32_bf16 v[2:5], v[172:175], v[218:221], v[2:5]
	v_mfma_f32_16x16x32_bf16 v[18:21], v[146:149], v[180:183], v[70:73]
	v_mfma_f32_16x16x32_bf16 v[22:25], v[172:175], v[180:183], v[66:69]
	v_mfma_f32_16x16x32_bf16 v[34:37], v[146:149], v[202:205], v[54:57]
	v_mfma_f32_16x16x32_bf16 v[38:41], v[172:175], v[202:205], v[50:53]
	v_mfma_f32_16x16x32_bf16 v[30:33], v[150:153], v[214:217], v[30:33]
	v_mfma_f32_16x16x32_bf16 v[26:29], v[176:179], v[214:217], v[26:29]
	v_mfma_f32_16x16x32_bf16 v[6:9], v[150:153], v[234:237], v[6:9]
	v_mfma_f32_16x16x32_bf16 v[2:5], v[176:179], v[234:237], v[2:5]
	v_mfma_f32_16x16x32_bf16 v[18:21], v[150:153], v[184:187], v[18:21]
	v_mfma_f32_16x16x32_bf16 v[22:25], v[176:179], v[184:187], v[22:25]
	v_mfma_f32_16x16x32_bf16 v[34:37], v[150:153], v[206:209], v[34:37]
	v_mfma_f32_16x16x32_bf16 v[38:41], v[176:179], v[206:209], v[38:41]
	s_setprio 0
	s_barrier
	s_add_i32 s17, 0, 0x18000
	v_add_u32_e32 v0, s17, v198
	s_add_i32 s18, 0, 0x1c000
	ds_read_b128 v[50:53], v0
	ds_read_b128 v[54:57], v0 offset:1024
	ds_read_b128 v[66:69], v0 offset:2048
	ds_read_b128 v[70:73], v0 offset:3072
	v_add_u32_e32 v0, s18, v198
	ds_read_b128 v[146:149], v0
	ds_read_b128 v[150:153], v0 offset:1024
	ds_read_b128 v[172:175], v0 offset:2048
	ds_read_b128 v[176:179], v0 offset:3072
	s_add_u32 s6, s6, 0x40000
	s_addc_u32 s7, s7, 0
	s_mov_b32 m0, s77
	ds_read_b128 v[180:183], v200 offset:32768
	ds_read_b128 v[184:187], v200 offset:33792
	ds_read_b128 v[202:205], v200 offset:34816
	ds_read_b128 v[206:209], v200 offset:35840
	ds_read_b128 v[210:213], v200 offset:36864
	ds_read_b128 v[214:217], v200 offset:37888
	ds_read_b128 v[218:221], v200 offset:38912
	ds_read_b128 v[234:237], v200 offset:39936
	global_load_lds_dwordx4 v160, s[6:7]
	s_mov_b32 m0, s96
	s_nop 0
	global_load_lds_dwordx4 v156, s[6:7]
	s_waitcnt vmcnt(8)
	s_waitcnt lgkmcnt(0)
	s_barrier
	s_setprio 1
	s_waitcnt lgkmcnt(0)
	v_mfma_f32_16x16x32_bf16 v[142:145], v[50:53], v[180:183], v[142:145]
	v_mfma_f32_16x16x32_bf16 v[138:141], v[66:69], v[180:183], v[138:141]
	v_mfma_f32_16x16x32_bf16 v[126:129], v[50:53], v[202:205], v[126:129]
	v_mfma_f32_16x16x32_bf16 v[122:125], v[66:69], v[202:205], v[122:125]
	v_mfma_f32_16x16x32_bf16 v[110:113], v[50:53], v[210:213], v[110:113]
	v_mfma_f32_16x16x32_bf16 v[106:109], v[66:69], v[210:213], v[106:109]
	v_mfma_f32_16x16x32_bf16 v[94:97], v[50:53], v[218:221], v[94:97]
	v_mfma_f32_16x16x32_bf16 v[90:93], v[66:69], v[218:221], v[90:93]
	v_mfma_f32_16x16x32_bf16 v[142:145], v[54:57], v[184:187], v[142:145]
	v_mfma_f32_16x16x32_bf16 v[138:141], v[70:73], v[184:187], v[138:141]
	v_mfma_f32_16x16x32_bf16 v[126:129], v[54:57], v[206:209], v[126:129]
	v_mfma_f32_16x16x32_bf16 v[122:125], v[70:73], v[206:209], v[122:125]
	v_mfma_f32_16x16x32_bf16 v[110:113], v[54:57], v[214:217], v[110:113]
	v_mfma_f32_16x16x32_bf16 v[106:109], v[70:73], v[214:217], v[106:109]
	v_mfma_f32_16x16x32_bf16 v[94:97], v[54:57], v[234:237], v[94:97]
	v_mfma_f32_16x16x32_bf16 v[90:93], v[70:73], v[234:237], v[90:93]
	s_setprio 0
	s_setprio 1
	v_mfma_f32_16x16x32_bf16 v[134:137], v[146:149], v[180:183], v[134:137]
	v_mfma_f32_16x16x32_bf16 v[130:133], v[172:175], v[180:183], v[130:133]
	v_mfma_f32_16x16x32_bf16 v[118:121], v[146:149], v[202:205], v[118:121]
	v_mfma_f32_16x16x32_bf16 v[114:117], v[172:175], v[202:205], v[114:117]
	v_mfma_f32_16x16x32_bf16 v[102:105], v[146:149], v[210:213], v[102:105]
	v_mfma_f32_16x16x32_bf16 v[98:101], v[172:175], v[210:213], v[98:101]
	v_mfma_f32_16x16x32_bf16 v[86:89], v[146:149], v[218:221], v[86:89]
	v_mfma_f32_16x16x32_bf16 v[82:85], v[172:175], v[218:221], v[82:85]
	v_mfma_f32_16x16x32_bf16 v[134:137], v[150:153], v[184:187], v[134:137]
	v_mfma_f32_16x16x32_bf16 v[130:133], v[176:179], v[184:187], v[130:133]
	v_mfma_f32_16x16x32_bf16 v[118:121], v[150:153], v[206:209], v[118:121]
	v_mfma_f32_16x16x32_bf16 v[114:117], v[176:179], v[206:209], v[114:117]
	v_mfma_f32_16x16x32_bf16 v[102:105], v[150:153], v[214:217], v[102:105]
	v_mfma_f32_16x16x32_bf16 v[98:101], v[176:179], v[214:217], v[98:101]
	v_mfma_f32_16x16x32_bf16 v[86:89], v[150:153], v[234:237], v[86:89]
	v_mfma_f32_16x16x32_bf16 v[82:85], v[176:179], v[234:237], v[82:85]
	s_setprio 0
	s_barrier
	s_add_i32 s6, s17, s87
	s_add_u32 vcc_lo, s4, s48
	s_addc_u32 vcc_hi, s5, s49
	s_mov_b32 m0, s6
	ds_read_b128 v[180:183], v200 offset:49152
	ds_read_b128 v[184:187], v200 offset:50176
	ds_read_b128 v[202:205], v200 offset:51200
	ds_read_b128 v[206:209], v200 offset:52224
	ds_read_b128 v[210:213], v200 offset:53248
	ds_read_b128 v[214:217], v200 offset:54272
	ds_read_b128 v[218:221], v200 offset:55296
	ds_read_b128 v[234:237], v200 offset:56320
	global_load_lds_dwordx4 v158, vcc
	s_add_i32 m0, s6, 0x2000
	s_add_u32 s4, s4, 0x40080
	s_addc_u32 s5, s5, 0
	s_add_i32 s6, s18, s87
	global_load_lds_dwordx4 v154, vcc
	s_mov_b32 m0, s6
	s_nop 0
	global_load_lds_dwordx4 v158, s[4:5]
	s_add_i32 m0, s6, 0x2000
	s_nop 0
	global_load_lds_dwordx4 v154, s[4:5]
	s_mov_b32 m0, s74
	s_nop 0
	global_load_lds_dwordx4 v160, s[98:99]
	s_mov_b32 m0, s75
	s_nop 0
	global_load_lds_dwordx4 v156, s[98:99]
	s_waitcnt vmcnt(8)
	s_waitcnt lgkmcnt(0)
	s_barrier
	s_setprio 1
	s_waitcnt lgkmcnt(0)
	v_mfma_f32_16x16x32_bf16 v[78:81], v[50:53], v[180:183], v[78:81]
	v_mfma_f32_16x16x32_bf16 v[74:77], v[66:69], v[180:183], v[74:77]
	v_mfma_f32_16x16x32_bf16 v[62:65], v[50:53], v[202:205], v[62:65]
	v_mfma_f32_16x16x32_bf16 v[58:61], v[66:69], v[202:205], v[58:61]
	v_mfma_f32_16x16x32_bf16 v[46:49], v[50:53], v[210:213], v[46:49]
	v_mfma_f32_16x16x32_bf16 v[42:45], v[66:69], v[210:213], v[42:45]
	v_mfma_f32_16x16x32_bf16 v[14:17], v[50:53], v[218:221], v[14:17]
	v_mfma_f32_16x16x32_bf16 v[10:13], v[66:69], v[218:221], v[10:13]
	v_mfma_f32_16x16x32_bf16 v[78:81], v[54:57], v[184:187], v[78:81]
	v_mfma_f32_16x16x32_bf16 v[74:77], v[70:73], v[184:187], v[74:77]
	v_mfma_f32_16x16x32_bf16 v[62:65], v[54:57], v[206:209], v[62:65]
	v_mfma_f32_16x16x32_bf16 v[58:61], v[70:73], v[206:209], v[58:61]
	v_mfma_f32_16x16x32_bf16 v[46:49], v[54:57], v[214:217], v[46:49]
	v_mfma_f32_16x16x32_bf16 v[42:45], v[70:73], v[214:217], v[42:45]
	v_mfma_f32_16x16x32_bf16 v[14:17], v[54:57], v[234:237], v[14:17]
	v_mfma_f32_16x16x32_bf16 v[10:13], v[70:73], v[234:237], v[10:13]
	s_setprio 0
	s_setprio 1
	v_mfma_f32_16x16x32_bf16 v[18:21], v[146:149], v[180:183], v[18:21]
	v_mfma_f32_16x16x32_bf16 v[70:73], v[150:153], v[184:187], v[18:21]
	v_mfma_f32_16x16x32_bf16 v[18:21], v[172:175], v[180:183], v[22:25]
	v_mfma_f32_16x16x32_bf16 v[66:69], v[176:179], v[184:187], v[18:21]
	v_mfma_f32_16x16x32_bf16 v[18:21], v[146:149], v[202:205], v[34:37]
	v_mfma_f32_16x16x32_bf16 v[54:57], v[150:153], v[206:209], v[18:21]
	v_mfma_f32_16x16x32_bf16 v[18:21], v[172:175], v[202:205], v[38:41]
	v_mfma_f32_16x16x32_bf16 v[50:53], v[176:179], v[206:209], v[18:21]
	v_mfma_f32_16x16x32_bf16 v[18:21], v[146:149], v[210:213], v[30:33]
	v_mfma_f32_16x16x32_bf16 v[30:33], v[150:153], v[214:217], v[18:21]
	v_mfma_f32_16x16x32_bf16 v[18:21], v[172:175], v[210:213], v[26:29]
	v_mfma_f32_16x16x32_bf16 v[6:9], v[146:149], v[218:221], v[6:9]
	v_mfma_f32_16x16x32_bf16 v[2:5], v[172:175], v[218:221], v[2:5]
	v_mfma_f32_16x16x32_bf16 v[26:29], v[176:179], v[214:217], v[18:21]
	v_mfma_f32_16x16x32_bf16 v[6:9], v[150:153], v[234:237], v[6:9]
	v_mfma_f32_16x16x32_bf16 v[2:5], v[176:179], v[234:237], v[2:5]
	s_setprio 0
	s_barrier
	s_add_i32 s16, s16, 2
	s_add_u32 s0, s0, 0x100
	s_addc_u32 s1, s1, 0
	s_add_u32 s14, s14, 0x100
	s_addc_u32 s15, s15, 0
	s_cmp_gt_u32 s16, 13
	s_cbranch_scc0 .LBB0_57
	v_readlane_b32 s0, v255, 4
	v_readlane_b32 s1, v255, 5
	s_and_b64 vcc, exec, s[0:1]
	s_cbranch_vccz .LBB0_60
	s_barrier
